# v13 + MLA attention loop unrolled by two tiles with LDS slot offsets as immediates, staging in the MFMA->VALU wait gap, last two tiles peeled
# speedup vs baseline: 1.0324x; 1.0065x over previous
; __device__ __forceinline__ float fexp2(float x) { return __builtin_amdgcn_exp2f(x); }
; template <int DQK, int DV>
; __device__ __forceinline__ void attn_pass2(const bf16_t* __restrict__ qh, const bf16_t* __restrict__ kh, const bf16_t* __restrict__ vth, int q0, char* smem, f32x16 (&o)[2][DV / 32], float kmax, int wvp) {
;     ...
;   for (int kt = 0; kt < NT; ++kt) {
;     const int cur = kt & 1;
;     __syncthreads();
;     if (kt + 1 < NT) { STOREKV(cur ^ 1); if (kt + 2 < NT) LOADKV(kt + 2); }
;     f32x16 s[2][2];
;     const char* kb0 = sK + cur * KSB + kofs;
; #pragma unroll
;     for (int ks = 0; ks < NKS; ++ks) {
;       const bf16x8 a0 = *(const bf16x8*)(kb0 + ks * 32), a1 = *(const bf16x8*)(kb0 + 32 * KP + ks * 32);
; #pragma unroll
;       for (int qb = 0; qb < 2; ++qb) {
;         if (ks == 0) {
;           f32x16 z;
; #pragma unroll
;           for (int i = 0; i < 16; ++i) z[i] = 0.f;
;           s[qb][0] = MFMA(a0, qf[qb][0], z); s[qb][1] = MFMA(a1, qf[qb][0], z);
;         } else { s[qb][0] = MFMA(a0, qf[qb][ks], s[qb][0]); s[qb][1] = MFMA(a1, qf[qb][ks], s[qb][1]); }
;       }
;     }
;     __builtin_amdgcn_sched_barrier(0);
; #pragma unroll
;     for (int qb = 0; qb < 2; ++qb) {
;       float rs0 = 0.f, rs1 = 0.f;
; #pragma unroll
;       for (int i = 0; i < 16; ++i) { s[qb][0][i] = fexp2(s[qb][0][i] - mref[qb]); s[qb][1][i] = fexp2(s[qb][1][i] - mref[qb]); rs0 += s[qb][0][i]; rs1 += s[qb][1][i]; }
;       l_run[qb] += rs0 + rs1;
;     }
;     const char* vb0 = sV + cur * VSB + vofs;
; #pragma unroll
;     for (int kb = 0; kb < 2; ++kb)
; #pragma unroll
;       for (int s2 = 0; s2 < 2; ++s2) {
;         bf16x8 pq[2];
; #pragma unroll
;         for (int qb = 0; qb < 2; ++qb) {
;           u32x4 w;
;           w.x = pk2(s[qb][kb][8 * s2 + 0], s[qb][kb][8 * s2 + 1]); w.y = pk2(s[qb][kb][8 * s2 + 2], s[qb][kb][8 * s2 + 3]);
;           w.z = pk2(s[qb][kb][8 * s2 + 4], s[qb][kb][8 * s2 + 5]); w.w = pk2(s[qb][kb][8 * s2 + 6], s[qb][kb][8 * s2 + 7]);
;           pq[qb] = __builtin_bit_cast(bf16x8, w);
;         }
; #pragma unroll
;         for (int eb = 0; eb < NEB; ++eb) {
;           const bf16x8 a = *(const bf16x8*)(vb0 + eb * 32 * VP + (32 * kb + 16 * s2) * 2);
; #pragma unroll
;           for (int qb = 0; qb < 2; ++qb) o[qb][eb] = MFMA(a, pq[qb], o[qb][eb]);
;         }
;       }
;   }
.LBB0_1446:
	s_waitcnt lgkmcnt(0)
	s_barrier
	ds_read_b128 v[64:67], v215
	ds_read_b128 v[202:205], v215 offset:32
	ds_read_b128 v[68:71], v215 offset:6656
	ds_read_b128 v[206:209], v215 offset:6688
	s_waitcnt lgkmcnt(3)
	v_mfma_f32_32x32x16_bf16 v[112:127], v[64:67], v[128:131], v[236:251]
	s_waitcnt lgkmcnt(1)
	v_mfma_f32_32x32x16_bf16 v[96:111], v[68:71], v[128:131], v[236:251]
	v_mfma_f32_32x32x16_bf16 v[80:95], v[64:67], v[152:155], v[236:251]
	v_mfma_f32_32x32x16_bf16 v[64:79], v[68:71], v[152:155], v[236:251]
	v_mfma_f32_32x32x16_bf16 v[112:127], v[202:205], v[132:135], v[112:127]
	s_waitcnt lgkmcnt(0)
	v_mfma_f32_32x32x16_bf16 v[96:111], v[206:209], v[132:135], v[96:111]
	v_mfma_f32_32x32x16_bf16 v[80:95], v[202:205], v[156:159], v[80:95]
	v_mfma_f32_32x32x16_bf16 v[64:79], v[206:209], v[156:159], v[64:79]
	ds_read_b128 v[202:205], v215 offset:64
	ds_read_b128 v[206:209], v215 offset:96
	ds_read_b128 v[218:221], v215 offset:6720
	ds_read_b128 v[222:225], v215 offset:6752
	s_waitcnt lgkmcnt(3)
	v_mfma_f32_32x32x16_bf16 v[112:127], v[202:205], v[136:139], v[112:127]
	s_waitcnt lgkmcnt(1)
	v_mfma_f32_32x32x16_bf16 v[96:111], v[218:221], v[136:139], v[96:111]
	v_mfma_f32_32x32x16_bf16 v[80:95], v[202:205], v[160:163], v[80:95]
	v_mfma_f32_32x32x16_bf16 v[64:79], v[218:221], v[160:163], v[64:79]
	v_mfma_f32_32x32x16_bf16 v[112:127], v[206:209], v[140:143], v[112:127]
	s_waitcnt lgkmcnt(0)
	v_mfma_f32_32x32x16_bf16 v[96:111], v[222:225], v[140:143], v[96:111]
	v_mfma_f32_32x32x16_bf16 v[80:95], v[206:209], v[164:167], v[80:95]
	ds_read_b128 v[202:205], v215 offset:128
	ds_read_b128 v[206:209], v215 offset:160
	v_mfma_f32_32x32x16_bf16 v[64:79], v[222:225], v[164:167], v[64:79]
	ds_read_b128 v[218:221], v215 offset:6784
	ds_read_b128 v[222:225], v215 offset:6816
	s_waitcnt lgkmcnt(3)
	v_mfma_f32_32x32x16_bf16 v[112:127], v[202:205], v[144:147], v[112:127]
	s_waitcnt lgkmcnt(1)
	v_mfma_f32_32x32x16_bf16 v[96:111], v[218:221], v[144:147], v[96:111]
	v_mfma_f32_32x32x16_bf16 v[80:95], v[202:205], v[168:171], v[80:95]
	v_mfma_f32_32x32x16_bf16 v[64:79], v[218:221], v[168:171], v[64:79]
	v_mfma_f32_32x32x16_bf16 v[112:127], v[206:209], v[148:151], v[112:127]
	s_waitcnt lgkmcnt(0)
	v_mfma_f32_32x32x16_bf16 v[96:111], v[222:225], v[148:151], v[96:111]
	v_mfma_f32_32x32x16_bf16 v[80:95], v[206:209], v[172:175], v[80:95]
	v_mfma_f32_32x32x16_bf16 v[64:79], v[222:225], v[172:175], v[64:79]
	s_waitcnt vmcnt(1)
	ds_write_b128 v212, v[180:183] offset:13312
	s_and_saveexec_b64 s[8:9], vcc
	ds_write_b128 v213, v[176:179] offset:13312
	s_or_b64 exec, exec, s[8:9]
	s_waitcnt vmcnt(0)
	ds_write_b128 v192, v[184:187] offset:35840
	v_lshl_add_u64 v[254:255], v[196:197], 0, s[6:7]
	global_load_dwordx4 v[180:183], v[254:255], off
	s_and_saveexec_b64 s[8:9], vcc
	v_lshl_add_u64 v[254:255], v[198:199], 0, s[6:7]
	global_load_dwordx4 v[176:179], v[254:255], off
	s_or_b64 exec, exec, s[8:9]
	global_load_dwordx4 v[184:187], v[194:195], off
	v_exp_f32_e32 v96, v96
	v_exp_f32_e32 v112, v112
	v_exp_f32_e32 v208, v97
	v_exp_f32_e32 v204, v113
	v_exp_f32_e32 v227, v99
	v_exp_f32_e32 v114, v114
	v_exp_f32_e32 v116, v116
	v_exp_f32_e32 v217, v98
	v_exp_f32_e32 v100, v100
	v_add_f32_e32 v98, v208, v96
	v_exp_f32_e32 v202, v117
	v_add_f32_e32 v97, v204, v112
	v_exp_f32_e32 v190, v115
	v_exp_f32_e32 v228, v101
	v_exp_f32_e32 v118, v118
	v_add_f32_e32 v98, v217, v98
	v_exp_f32_e32 v229, v102
	v_add_f32_e32 v97, v114, v97
	v_add_f32_e32 v98, v227, v98
	v_add_f32_e32 v97, v190, v97
	v_add_f32_e32 v98, v100, v98
	v_add_f32_e32 v97, v116, v97
	v_add_f32_e32 v98, v228, v98
	v_add_f32_e32 v97, v202, v97
	v_add_f32_e32 v113, v229, v98
	v_add_f32_e32 v115, v118, v97
	v_exp_f32_e32 v203, v119
	v_exp_f32_e32 v119, v121
	v_exp_f32_e32 v117, v105
	v_exp_f32_e32 v99, v122
	v_exp_f32_e32 v101, v106
	v_exp_f32_e32 v205, v103
	v_exp_f32_e32 v103, v123
	v_exp_f32_e32 v105, v107
	v_exp_f32_e32 v107, v124
	v_exp_f32_e32 v121, v108
	v_exp_f32_e32 v125, v125
	v_exp_f32_e32 v109, v109
	v_exp_f32_e32 v123, v126
	v_exp_f32_e32 v209, v110
	v_exp_f32_e32 v127, v127
	v_exp_f32_e32 v98, v80
	v_exp_f32_e32 v102, v81
	v_exp_f32_e32 v108, v65
	v_exp_f32_e32 v207, v120
	v_exp_f32_e32 v97, v104
	v_exp_f32_e32 v104, v64
	v_exp_f32_e32 v106, v82
	v_exp_f32_e32 v111, v111
	v_exp_f32_e32 v110, v66
	v_add_f32_e32 v64, v102, v98
	v_add_f32_e32 v120, v106, v64
	v_add_f32_e32 v65, v108, v104
	v_exp_f32_e32 v231, v83
	v_add_f32_e32 v230, v110, v65
	v_mov_b32_e32 v122, v67
	v_exp_f32_e32 v232, v84
	ds_read_b128 v[64:67], v216 offset:26624
	ds_read_b128 v[218:221], v216 offset:26656
	v_exp_f32_e32 v234, v85
	ds_read_b128 v[222:225], v216 offset:31232
	v_exp_f32_e32 v235, v86
	v_cvt_pk_bf16_f32 v82, v116, v202
	v_exp_f32_e32 v202, v87
	v_cvt_pk_bf16_f32 v80, v112, v204
	v_cvt_pk_bf16_f32 v81, v114, v190
	v_cvt_pk_bf16_f32 v83, v118, v203
	v_cvt_pk_bf16_f32 v84, v98, v102
	v_cvt_pk_bf16_f32 v85, v106, v231
	v_cvt_pk_bf16_f32 v86, v232, v234
	v_cvt_pk_bf16_f32 v87, v235, v202
	s_waitcnt lgkmcnt(2)
	v_mfma_f32_32x32x16_bf16 v[48:63], v[64:67], v[80:83], v[48:63]
	v_exp_f32_e32 v116, v122
	s_add_u32 s6, s6, 0x3000
	s_addc_u32 s7, s7, 0
	v_mfma_f32_32x32x16_bf16 v[16:31], v[64:67], v[84:87], v[16:31]
	v_exp_f32_e32 v190, v68
	v_exp_f32_e32 v206, v88
	ds_read_b128 v[64:67], v216 offset:31264
	v_exp_f32_e32 v118, v89
	s_waitcnt lgkmcnt(1)
; __device__ __forceinline__ float fexp2(float x) { return __builtin_amdgcn_exp2f(x); }
; template <int DQK, int DV>
; __device__ __forceinline__ void attn_pass2(const bf16_t* __restrict__ qh, const bf16_t* __restrict__ kh, const bf16_t* __restrict__ vth, int q0, char* smem, f32x16 (&o)[2][DV / 32], float kmax, int wvp) {
;     ...
;   for (int kt = 0; kt < NT; ++kt) {
;     const int cur = kt & 1;
;     __syncthreads();
;     if (kt + 1 < NT) { STOREKV(cur ^ 1); if (kt + 2 < NT) LOADKV(kt + 2); }
;     f32x16 s[2][2];
;     const char* kb0 = sK + cur * KSB + kofs;
; #pragma unroll
;     for (int ks = 0; ks < NKS; ++ks) {
;       const bf16x8 a0 = *(const bf16x8*)(kb0 + ks * 32), a1 = *(const bf16x8*)(kb0 + 32 * KP + ks * 32);
; #pragma unroll
;       for (int qb = 0; qb < 2; ++qb) {
;         if (ks == 0) {
;           f32x16 z;
; #pragma unroll
;           for (int i = 0; i < 16; ++i) z[i] = 0.f;
;           s[qb][0] = MFMA(a0, qf[qb][0], z); s[qb][1] = MFMA(a1, qf[qb][0], z);
;         } else { s[qb][0] = MFMA(a0, qf[qb][ks], s[qb][0]); s[qb][1] = MFMA(a1, qf[qb][ks], s[qb][1]); }
;       }
;     }
;     __builtin_amdgcn_sched_barrier(0);
; #pragma unroll
;     for (int qb = 0; qb < 2; ++qb) {
;       float rs0 = 0.f, rs1 = 0.f;
; #pragma unroll
;       for (int i = 0; i < 16; ++i) { s[qb][0][i] = fexp2(s[qb][0][i] - mref[qb]); s[qb][1][i] = fexp2(s[qb][1][i] - mref[qb]); rs0 += s[qb][0][i]; rs1 += s[qb][1][i]; }
;       l_run[qb] += rs0 + rs1;
;     }
;     const char* vb0 = sV + cur * VSB + vofs;
; #pragma unroll
;     for (int kb = 0; kb < 2; ++kb)
; #pragma unroll
;       for (int s2 = 0; s2 < 2; ++s2) {
;         bf16x8 pq[2];
; #pragma unroll
;         for (int qb = 0; qb < 2; ++qb) {
;           u32x4 w;
;           w.x = pk2(s[qb][kb][8 * s2 + 0], s[qb][kb][8 * s2 + 1]); w.y = pk2(s[qb][kb][8 * s2 + 2], s[qb][kb][8 * s2 + 3]);
;           w.z = pk2(s[qb][kb][8 * s2 + 4], s[qb][kb][8 * s2 + 5]); w.w = pk2(s[qb][kb][8 * s2 + 6], s[qb][kb][8 * s2 + 7]);
;           pq[qb] = __builtin_bit_cast(bf16x8, w);
;         }
; #pragma unroll
;         for (int eb = 0; eb < NEB; ++eb) {
;           const bf16x8 a = *(const bf16x8*)(vb0 + eb * 32 * VP + (32 * kb + 16 * s2) * 2);
; #pragma unroll
;           for (int qb = 0; qb < 2; ++qb) o[qb][eb] = MFMA(a, pq[qb], o[qb][eb]);
;         }
;       }
;   }
	v_mfma_f32_32x32x16_bf16 v[32:47], v[222:225], v[80:83], v[32:47]
	v_exp_f32_e32 v98, v90
	v_exp_f32_e32 v102, v91
	v_exp_f32_e32 v106, v92
	v_exp_f32_e32 v124, v93
	v_mfma_f32_32x32x16_bf16 v[0:15], v[222:225], v[84:87], v[0:15]
	v_exp_f32_e32 v122, v94
	v_exp_f32_e32 v89, v69
	v_exp_f32_e32 v126, v95
	v_exp_f32_e32 v90, v70
	v_cvt_pk_bf16_f32 v80, v207, v119
	v_cvt_pk_bf16_f32 v81, v99, v103
	v_cvt_pk_bf16_f32 v82, v107, v125
	v_cvt_pk_bf16_f32 v83, v123, v127
	v_add_f32_e32 v68, v231, v120
	v_add_f32_e32 v88, v116, v230
	v_mfma_f32_32x32x16_bf16 v[48:63], v[218:221], v[80:83], v[48:63]
	v_add_f32_e32 v68, v232, v68
	v_add_f32_e32 v88, v190, v88
	v_add_f32_e32 v68, v234, v68
	v_add_f32_e32 v69, v89, v88
	v_cvt_pk_bf16_f32 v84, v206, v118
	v_cvt_pk_bf16_f32 v85, v98, v102
	v_cvt_pk_bf16_f32 v86, v106, v124
	s_waitcnt lgkmcnt(0)
	v_mfma_f32_32x32x16_bf16 v[32:47], v[64:67], v[80:83], v[32:47]
	v_exp_f32_e32 v204, v71
	v_cvt_pk_bf16_f32 v87, v122, v126
	v_add_f32_e32 v114, v235, v68
	v_add_f32_e32 v112, v90, v69
	ds_read_b128 v[68:71], v216 offset:26688
	ds_read_b128 v[80:83], v216 offset:26720
	v_mfma_f32_32x32x16_bf16 v[16:31], v[218:221], v[84:87], v[16:31]
	v_lshl_add_u64 v[194:195], v[194:195], 0, s[54:55]
	v_mfma_f32_32x32x16_bf16 v[0:15], v[64:67], v[84:87], v[0:15]
	v_cvt_pk_bf16_f32 v86, v190, v89
	v_cvt_pk_bf16_f32 v87, v90, v204
	ds_read_b128 v[88:91], v216 offset:31296
	v_cvt_pk_bf16_f32 v64, v96, v208
	v_cvt_pk_bf16_f32 v65, v217, v227
	v_cvt_pk_bf16_f32 v66, v100, v228
	v_cvt_pk_bf16_f32 v67, v229, v205
	v_cvt_pk_bf16_f32 v84, v104, v108
	v_cvt_pk_bf16_f32 v85, v110, v116
	s_waitcnt lgkmcnt(2)
	v_mfma_f32_32x32x16_bf16 v[48:63], v[68:71], v[64:67], v[48:63]
	v_exp_f32_e32 v96, v72
	v_exp_f32_e32 v116, v73
	v_exp_f32_e32 v120, v76
	v_add_f32_e32 v72, v204, v112
	v_add_f32_e32 v73, v205, v113
	v_mfma_f32_32x32x16_bf16 v[16:31], v[68:71], v[84:87], v[16:31]
	v_exp_f32_e32 v100, v74
	v_exp_f32_e32 v104, v75
	ds_read_b128 v[68:71], v216 offset:31328
	v_add_f32_e32 v72, v96, v72
	v_add_f32_e32 v73, v97, v73
	s_waitcnt lgkmcnt(1)
	v_mfma_f32_32x32x16_bf16 v[32:47], v[88:91], v[64:67], v[32:47]
	v_exp_f32_e32 v108, v77
	v_exp_f32_e32 v208, v78
	v_exp_f32_e32 v110, v79
	v_add_f32_e32 v64, v202, v114
	v_add_f32_e32 v65, v203, v115
	v_mfma_f32_32x32x16_bf16 v[0:15], v[88:91], v[84:87], v[0:15]
	v_add_f32_e64 v74, v206, v64
	v_add_f32_e64 v75, v207, v65
	v_cvt_pk_bf16_f32 v64, v97, v117
	v_cvt_pk_bf16_f32 v65, v101, v105
	v_cvt_pk_bf16_f32 v66, v121, v109
	v_cvt_pk_bf16_f32 v67, v209, v111
	v_add_f32_e32 v76, v118, v74
	v_add_f32_e32 v77, v119, v75
	v_add_f32_e32 v78, v116, v72
	v_add_f32_e32 v79, v117, v73
	v_cvt_pk_bf16_f32 v72, v96, v116
	v_cvt_pk_bf16_f32 v73, v100, v104
	v_cvt_pk_bf16_f32 v74, v120, v108
	v_cvt_pk_bf16_f32 v75, v208, v110
	v_mfma_f32_32x32x16_bf16 v[48:63], v[80:83], v[64:67], v[48:63]
	v_add_f32_e64 v76, v98, v76
	v_add_f32_e64 v77, v99, v77
	v_add_f32_e64 v78, v100, v78
	v_add_f32_e64 v79, v101, v79
	v_add_f32_e64 v76, v102, v76
	v_add_f32_e64 v77, v103, v77
	v_add_f32_e32 v78, v104, v78
	v_add_f32_e32 v79, v105, v79
	v_add_f32_e32 v76, v106, v76
	v_add_f32_e32 v77, v107, v77
	v_add_f32_e32 v78, v120, v78
	v_add_f32_e32 v79, v121, v79
	v_add_f32_e32 v76, v124, v76
	v_add_f32_e32 v77, v125, v77
	v_mfma_f32_32x32x16_bf16 v[16:31], v[80:83], v[72:75], v[16:31]
	s_waitcnt lgkmcnt(0)
	v_mfma_f32_32x32x16_bf16 v[32:47], v[68:71], v[64:67], v[32:47]
	v_add_f32_e64 v64, v108, v78
	v_add_f32_e64 v65, v109, v79
	v_add_f32_e64 v66, v122, v76
	v_add_f32_e64 v67, v123, v77
	v_add_f32_e64 v64, v208, v64
	v_add_f32_e64 v65, v209, v65
	v_add_f32_e32 v66, v126, v66
	v_add_f32_e32 v67, v127, v67
	v_add_f32_e32 v64, v110, v64
	v_add_f32_e32 v65, v111, v65
	s_nop 0
	v_add_f32_e32 v64, v66, v64
	v_add_f32_e32 v65, v67, v65
	v_mfma_f32_32x32x16_bf16 v[0:15], v[68:71], v[72:75], v[0:15]
	v_add_f32_e64 v200, v200, v64
	v_add_f32_e64 v201, v201, v65
	s_waitcnt lgkmcnt(0)
	s_barrier
	ds_read_b128 v[64:67], v215 offset:13312
	ds_read_b128 v[202:205], v215 offset:13344
	ds_read_b128 v[68:71], v215 offset:19968
	ds_read_b128 v[206:209], v215 offset:20000
	s_waitcnt lgkmcnt(3)
	v_mfma_f32_32x32x16_bf16 v[112:127], v[64:67], v[128:131], v[236:251]
	s_waitcnt lgkmcnt(1)
	v_mfma_f32_32x32x16_bf16 v[96:111], v[68:71], v[128:131], v[236:251]
	v_mfma_f32_32x32x16_bf16 v[80:95], v[64:67], v[152:155], v[236:251]
	v_mfma_f32_32x32x16_bf16 v[64:79], v[68:71], v[152:155], v[236:251]
	v_mfma_f32_32x32x16_bf16 v[112:127], v[202:205], v[132:135], v[112:127]
	s_waitcnt lgkmcnt(0)
	v_mfma_f32_32x32x16_bf16 v[96:111], v[206:209], v[132:135], v[96:111]
	v_mfma_f32_32x32x16_bf16 v[80:95], v[202:205], v[156:159], v[80:95]
	v_mfma_f32_32x32x16_bf16 v[64:79], v[206:209], v[156:159], v[64:79]
	ds_read_b128 v[202:205], v215 offset:13376
	ds_read_b128 v[206:209], v215 offset:13408
	ds_read_b128 v[218:221], v215 offset:20032
	ds_read_b128 v[222:225], v215 offset:20064
	s_waitcnt lgkmcnt(3)
	v_mfma_f32_32x32x16_bf16 v[112:127], v[202:205], v[136:139], v[112:127]
	s_waitcnt lgkmcnt(1)
	v_mfma_f32_32x32x16_bf16 v[96:111], v[218:221], v[136:139], v[96:111]
	v_mfma_f32_32x32x16_bf16 v[80:95], v[202:205], v[160:163], v[80:95]
	v_mfma_f32_32x32x16_bf16 v[64:79], v[218:221], v[160:163], v[64:79]
	v_mfma_f32_32x32x16_bf16 v[112:127], v[206:209], v[140:143], v[112:127]
	s_waitcnt lgkmcnt(0)
	v_mfma_f32_32x32x16_bf16 v[96:111], v[222:225], v[140:143], v[96:111]
	v_mfma_f32_32x32x16_bf16 v[80:95], v[206:209], v[164:167], v[80:95]
	ds_read_b128 v[202:205], v215 offset:13440
	ds_read_b128 v[206:209], v215 offset:13472
	v_mfma_f32_32x32x16_bf16 v[64:79], v[222:225], v[164:167], v[64:79]
	ds_read_b128 v[218:221], v215 offset:20096
	ds_read_b128 v[222:225], v215 offset:20128
	s_waitcnt lgkmcnt(3)
; __device__ __forceinline__ float fexp2(float x) { return __builtin_amdgcn_exp2f(x); }
; template <int DQK, int DV>
; __device__ __forceinline__ void attn_pass2(const bf16_t* __restrict__ qh, const bf16_t* __restrict__ kh, const bf16_t* __restrict__ vth, int q0, char* smem, f32x16 (&o)[2][DV / 32], float kmax, int wvp) {
;     ...
;   for (int kt = 0; kt < NT; ++kt) {
;     const int cur = kt & 1;
;     __syncthreads();
;     if (kt + 1 < NT) { STOREKV(cur ^ 1); if (kt + 2 < NT) LOADKV(kt + 2); }
;     f32x16 s[2][2];
;     const char* kb0 = sK + cur * KSB + kofs;
; #pragma unroll
;     for (int ks = 0; ks < NKS; ++ks) {
;       const bf16x8 a0 = *(const bf16x8*)(kb0 + ks * 32), a1 = *(const bf16x8*)(kb0 + 32 * KP + ks * 32);
; #pragma unroll
;       for (int qb = 0; qb < 2; ++qb) {
;         if (ks == 0) {
;           f32x16 z;
; #pragma unroll
;           for (int i = 0; i < 16; ++i) z[i] = 0.f;
;           s[qb][0] = MFMA(a0, qf[qb][0], z); s[qb][1] = MFMA(a1, qf[qb][0], z);
;         } else { s[qb][0] = MFMA(a0, qf[qb][ks], s[qb][0]); s[qb][1] = MFMA(a1, qf[qb][ks], s[qb][1]); }
;       }
;     }
;     __builtin_amdgcn_sched_barrier(0);
; #pragma unroll
;     for (int qb = 0; qb < 2; ++qb) {
;       float rs0 = 0.f, rs1 = 0.f;
; #pragma unroll
;       for (int i = 0; i < 16; ++i) { s[qb][0][i] = fexp2(s[qb][0][i] - mref[qb]); s[qb][1][i] = fexp2(s[qb][1][i] - mref[qb]); rs0 += s[qb][0][i]; rs1 += s[qb][1][i]; }
;       l_run[qb] += rs0 + rs1;
;     }
;     const char* vb0 = sV + cur * VSB + vofs;
; #pragma unroll
;     for (int kb = 0; kb < 2; ++kb)
; #pragma unroll
;       for (int s2 = 0; s2 < 2; ++s2) {
;         bf16x8 pq[2];
; #pragma unroll
;         for (int qb = 0; qb < 2; ++qb) {
;           u32x4 w;
;           w.x = pk2(s[qb][kb][8 * s2 + 0], s[qb][kb][8 * s2 + 1]); w.y = pk2(s[qb][kb][8 * s2 + 2], s[qb][kb][8 * s2 + 3]);
;           w.z = pk2(s[qb][kb][8 * s2 + 4], s[qb][kb][8 * s2 + 5]); w.w = pk2(s[qb][kb][8 * s2 + 6], s[qb][kb][8 * s2 + 7]);
;           pq[qb] = __builtin_bit_cast(bf16x8, w);
;         }
; #pragma unroll
;         for (int eb = 0; eb < NEB; ++eb) {
;           const bf16x8 a = *(const bf16x8*)(vb0 + eb * 32 * VP + (32 * kb + 16 * s2) * 2);
; #pragma unroll
;           for (int qb = 0; qb < 2; ++qb) o[qb][eb] = MFMA(a, pq[qb], o[qb][eb]);
;         }
;       }
;   }
	v_mfma_f32_32x32x16_bf16 v[112:127], v[202:205], v[144:147], v[112:127]
	s_waitcnt lgkmcnt(1)
	v_mfma_f32_32x32x16_bf16 v[96:111], v[218:221], v[144:147], v[96:111]
	v_mfma_f32_32x32x16_bf16 v[80:95], v[202:205], v[168:171], v[80:95]
	v_mfma_f32_32x32x16_bf16 v[64:79], v[218:221], v[168:171], v[64:79]
	v_mfma_f32_32x32x16_bf16 v[112:127], v[206:209], v[148:151], v[112:127]
	s_waitcnt lgkmcnt(0)
	v_mfma_f32_32x32x16_bf16 v[96:111], v[222:225], v[148:151], v[96:111]
	v_mfma_f32_32x32x16_bf16 v[80:95], v[206:209], v[172:175], v[80:95]
	v_mfma_f32_32x32x16_bf16 v[64:79], v[222:225], v[172:175], v[64:79]
	s_waitcnt vmcnt(1)
	ds_write_b128 v212, v[180:183]
	s_and_saveexec_b64 s[8:9], vcc
	ds_write_b128 v213, v[176:179]
	s_or_b64 exec, exec, s[8:9]
	s_waitcnt vmcnt(0)
	ds_write_b128 v192, v[184:187] offset:26624
	v_lshl_add_u64 v[254:255], v[196:197], 0, s[6:7]
	global_load_dwordx4 v[180:183], v[254:255], off
	s_and_saveexec_b64 s[8:9], vcc
	v_lshl_add_u64 v[254:255], v[198:199], 0, s[6:7]
	global_load_dwordx4 v[176:179], v[254:255], off
	s_or_b64 exec, exec, s[8:9]
	global_load_dwordx4 v[184:187], v[194:195], off
	v_exp_f32_e32 v96, v96
	v_exp_f32_e32 v112, v112
	v_exp_f32_e32 v208, v97
	v_exp_f32_e32 v204, v113
	v_exp_f32_e32 v227, v99
	v_exp_f32_e32 v114, v114
	v_exp_f32_e32 v116, v116
	v_exp_f32_e32 v217, v98
	v_exp_f32_e32 v100, v100
	v_add_f32_e32 v98, v208, v96
	v_exp_f32_e32 v202, v117
	v_add_f32_e32 v97, v204, v112
	v_exp_f32_e32 v190, v115
	v_exp_f32_e32 v228, v101
	v_exp_f32_e32 v118, v118
	v_add_f32_e32 v98, v217, v98
	v_exp_f32_e32 v229, v102
	v_add_f32_e32 v97, v114, v97
	v_add_f32_e32 v98, v227, v98
	v_add_f32_e32 v97, v190, v97
	v_add_f32_e32 v98, v100, v98
	v_add_f32_e32 v97, v116, v97
	v_add_f32_e32 v98, v228, v98
	v_add_f32_e32 v97, v202, v97
	v_add_f32_e32 v113, v229, v98
	v_add_f32_e32 v115, v118, v97
	v_exp_f32_e32 v203, v119
	v_exp_f32_e32 v119, v121
	v_exp_f32_e32 v117, v105
	v_exp_f32_e32 v99, v122
	v_exp_f32_e32 v101, v106
	v_exp_f32_e32 v205, v103
	v_exp_f32_e32 v103, v123
	v_exp_f32_e32 v105, v107
	v_exp_f32_e32 v107, v124
	v_exp_f32_e32 v121, v108
	v_exp_f32_e32 v125, v125
	v_exp_f32_e32 v109, v109
	v_exp_f32_e32 v123, v126
	v_exp_f32_e32 v209, v110
	v_exp_f32_e32 v127, v127
	v_exp_f32_e32 v98, v80
	v_exp_f32_e32 v102, v81
	v_exp_f32_e32 v108, v65
	v_exp_f32_e32 v207, v120
	v_exp_f32_e32 v97, v104
	v_exp_f32_e32 v104, v64
	v_exp_f32_e32 v106, v82
	v_exp_f32_e32 v111, v111
	v_exp_f32_e32 v110, v66
	v_add_f32_e32 v64, v102, v98
	v_add_f32_e32 v120, v106, v64
	v_add_f32_e32 v65, v108, v104
	v_exp_f32_e32 v231, v83
	v_add_f32_e32 v230, v110, v65
	v_mov_b32_e32 v122, v67
	v_exp_f32_e32 v232, v84
	ds_read_b128 v[64:67], v216 offset:35840
	ds_read_b128 v[218:221], v216 offset:35872
	v_exp_f32_e32 v234, v85
	ds_read_b128 v[222:225], v216 offset:40448
	v_exp_f32_e32 v235, v86
	v_cvt_pk_bf16_f32 v82, v116, v202
	v_exp_f32_e32 v202, v87
	v_cvt_pk_bf16_f32 v80, v112, v204
	v_cvt_pk_bf16_f32 v81, v114, v190
	v_cvt_pk_bf16_f32 v83, v118, v203
	v_cvt_pk_bf16_f32 v84, v98, v102
	v_cvt_pk_bf16_f32 v85, v106, v231
	v_cvt_pk_bf16_f32 v86, v232, v234
	v_cvt_pk_bf16_f32 v87, v235, v202
	s_waitcnt lgkmcnt(2)
	v_mfma_f32_32x32x16_bf16 v[48:63], v[64:67], v[80:83], v[48:63]
	v_exp_f32_e32 v116, v122
	s_add_u32 s6, s6, 0x3000
	s_addc_u32 s7, s7, 0
	v_mfma_f32_32x32x16_bf16 v[16:31], v[64:67], v[84:87], v[16:31]
	v_exp_f32_e32 v190, v68
	v_exp_f32_e32 v206, v88
	ds_read_b128 v[64:67], v216 offset:40480
	v_exp_f32_e32 v118, v89
	s_waitcnt lgkmcnt(1)
	v_mfma_f32_32x32x16_bf16 v[32:47], v[222:225], v[80:83], v[32:47]
	v_exp_f32_e32 v98, v90
	v_exp_f32_e32 v102, v91
	v_exp_f32_e32 v106, v92
	v_exp_f32_e32 v124, v93
	v_mfma_f32_32x32x16_bf16 v[0:15], v[222:225], v[84:87], v[0:15]
	v_exp_f32_e32 v122, v94
	v_exp_f32_e32 v89, v69
	v_exp_f32_e32 v126, v95
	v_exp_f32_e32 v90, v70
	v_cvt_pk_bf16_f32 v80, v207, v119
	v_cvt_pk_bf16_f32 v81, v99, v103
	v_cvt_pk_bf16_f32 v82, v107, v125
	v_cvt_pk_bf16_f32 v83, v123, v127
	v_add_f32_e32 v68, v231, v120
	v_add_f32_e32 v88, v116, v230
	v_mfma_f32_32x32x16_bf16 v[48:63], v[218:221], v[80:83], v[48:63]
	v_add_f32_e32 v68, v232, v68
	v_add_f32_e32 v88, v190, v88
	v_add_f32_e32 v68, v234, v68
	v_add_f32_e32 v69, v89, v88
	v_cvt_pk_bf16_f32 v84, v206, v118
	v_cvt_pk_bf16_f32 v85, v98, v102
	v_cvt_pk_bf16_f32 v86, v106, v124
	s_waitcnt lgkmcnt(0)
	v_mfma_f32_32x32x16_bf16 v[32:47], v[64:67], v[80:83], v[32:47]
	v_exp_f32_e32 v204, v71
	v_cvt_pk_bf16_f32 v87, v122, v126
	v_add_f32_e32 v114, v235, v68
	v_add_f32_e32 v112, v90, v69
	ds_read_b128 v[68:71], v216 offset:35904
	ds_read_b128 v[80:83], v216 offset:35936
	v_mfma_f32_32x32x16_bf16 v[16:31], v[218:221], v[84:87], v[16:31]
	v_lshl_add_u64 v[194:195], v[194:195], 0, s[54:55]
	v_mfma_f32_32x32x16_bf16 v[0:15], v[64:67], v[84:87], v[0:15]
	v_cvt_pk_bf16_f32 v86, v190, v89
	v_cvt_pk_bf16_f32 v87, v90, v204
	ds_read_b128 v[88:91], v216 offset:40512
	v_cvt_pk_bf16_f32 v64, v96, v208
	v_cvt_pk_bf16_f32 v65, v217, v227
	v_cvt_pk_bf16_f32 v66, v100, v228
	v_cvt_pk_bf16_f32 v67, v229, v205
	v_cvt_pk_bf16_f32 v84, v104, v108
	v_cvt_pk_bf16_f32 v85, v110, v116
	s_waitcnt lgkmcnt(2)
	v_mfma_f32_32x32x16_bf16 v[48:63], v[68:71], v[64:67], v[48:63]
	v_exp_f32_e32 v96, v72
	v_exp_f32_e32 v116, v73
	v_exp_f32_e32 v120, v76
	v_add_f32_e32 v72, v204, v112
	v_add_f32_e32 v73, v205, v113
	v_mfma_f32_32x32x16_bf16 v[16:31], v[68:71], v[84:87], v[16:31]
	v_exp_f32_e32 v100, v74
	v_exp_f32_e32 v104, v75
	ds_read_b128 v[68:71], v216 offset:40544
	v_add_f32_e32 v72, v96, v72
	v_add_f32_e32 v73, v97, v73
	s_waitcnt lgkmcnt(1)
; __device__ __forceinline__ float fexp2(float x) { return __builtin_amdgcn_exp2f(x); }
; template <int DQK, int DV>
; __device__ __forceinline__ void attn_pass2(const bf16_t* __restrict__ qh, const bf16_t* __restrict__ kh, const bf16_t* __restrict__ vth, int q0, char* smem, f32x16 (&o)[2][DV / 32], float kmax, int wvp) {
;     ...
;   for (int kt = 0; kt < NT; ++kt) {
;     const int cur = kt & 1;
;     __syncthreads();
;     if (kt + 1 < NT) { STOREKV(cur ^ 1); if (kt + 2 < NT) LOADKV(kt + 2); }
;     f32x16 s[2][2];
;     const char* kb0 = sK + cur * KSB + kofs;
; #pragma unroll
;     for (int ks = 0; ks < NKS; ++ks) {
;       const bf16x8 a0 = *(const bf16x8*)(kb0 + ks * 32), a1 = *(const bf16x8*)(kb0 + 32 * KP + ks * 32);
; #pragma unroll
;       for (int qb = 0; qb < 2; ++qb) {
;         if (ks == 0) {
;           f32x16 z;
; #pragma unroll
;           for (int i = 0; i < 16; ++i) z[i] = 0.f;
;           s[qb][0] = MFMA(a0, qf[qb][0], z); s[qb][1] = MFMA(a1, qf[qb][0], z);
;         } else { s[qb][0] = MFMA(a0, qf[qb][ks], s[qb][0]); s[qb][1] = MFMA(a1, qf[qb][ks], s[qb][1]); }
;       }
;     }
;     __builtin_amdgcn_sched_barrier(0);
; #pragma unroll
;     for (int qb = 0; qb < 2; ++qb) {
;       float rs0 = 0.f, rs1 = 0.f;
; #pragma unroll
;       for (int i = 0; i < 16; ++i) { s[qb][0][i] = fexp2(s[qb][0][i] - mref[qb]); s[qb][1][i] = fexp2(s[qb][1][i] - mref[qb]); rs0 += s[qb][0][i]; rs1 += s[qb][1][i]; }
;       l_run[qb] += rs0 + rs1;
;     }
;     const char* vb0 = sV + cur * VSB + vofs;
; #pragma unroll
;     for (int kb = 0; kb < 2; ++kb)
; #pragma unroll
;       for (int s2 = 0; s2 < 2; ++s2) {
;         bf16x8 pq[2];
; #pragma unroll
;         for (int qb = 0; qb < 2; ++qb) {
;           u32x4 w;
;           w.x = pk2(s[qb][kb][8 * s2 + 0], s[qb][kb][8 * s2 + 1]); w.y = pk2(s[qb][kb][8 * s2 + 2], s[qb][kb][8 * s2 + 3]);
;           w.z = pk2(s[qb][kb][8 * s2 + 4], s[qb][kb][8 * s2 + 5]); w.w = pk2(s[qb][kb][8 * s2 + 6], s[qb][kb][8 * s2 + 7]);
;           pq[qb] = __builtin_bit_cast(bf16x8, w);
;         }
; #pragma unroll
;         for (int eb = 0; eb < NEB; ++eb) {
;           const bf16x8 a = *(const bf16x8*)(vb0 + eb * 32 * VP + (32 * kb + 16 * s2) * 2);
; #pragma unroll
;           for (int qb = 0; qb < 2; ++qb) o[qb][eb] = MFMA(a, pq[qb], o[qb][eb]);
;         }
;       }
;   }
	v_mfma_f32_32x32x16_bf16 v[32:47], v[88:91], v[64:67], v[32:47]
	v_exp_f32_e32 v108, v77
	v_exp_f32_e32 v208, v78
	v_exp_f32_e32 v110, v79
	v_add_f32_e32 v64, v202, v114
	v_add_f32_e32 v65, v203, v115
	v_mfma_f32_32x32x16_bf16 v[0:15], v[88:91], v[84:87], v[0:15]
	v_add_f32_e64 v74, v206, v64
	v_add_f32_e64 v75, v207, v65
	v_cvt_pk_bf16_f32 v64, v97, v117
	v_cvt_pk_bf16_f32 v65, v101, v105
	v_cvt_pk_bf16_f32 v66, v121, v109
	v_cvt_pk_bf16_f32 v67, v209, v111
	v_add_f32_e32 v76, v118, v74
	v_add_f32_e32 v77, v119, v75
	v_add_f32_e32 v78, v116, v72
	v_add_f32_e32 v79, v117, v73
	v_cvt_pk_bf16_f32 v72, v96, v116
	v_cvt_pk_bf16_f32 v73, v100, v104
	v_cvt_pk_bf16_f32 v74, v120, v108
	v_cvt_pk_bf16_f32 v75, v208, v110
	v_mfma_f32_32x32x16_bf16 v[48:63], v[80:83], v[64:67], v[48:63]
	v_add_f32_e64 v76, v98, v76
	v_add_f32_e64 v77, v99, v77
	v_add_f32_e64 v78, v100, v78
	v_add_f32_e64 v79, v101, v79
	v_add_f32_e64 v76, v102, v76
	v_add_f32_e64 v77, v103, v77
	v_add_f32_e32 v78, v104, v78
	v_add_f32_e32 v79, v105, v79
	v_add_f32_e32 v76, v106, v76
	v_add_f32_e32 v77, v107, v77
	v_add_f32_e32 v78, v120, v78
	v_add_f32_e32 v79, v121, v79
	v_add_f32_e32 v76, v124, v76
	v_add_f32_e32 v77, v125, v77
	v_mfma_f32_32x32x16_bf16 v[16:31], v[80:83], v[72:75], v[16:31]
	s_waitcnt lgkmcnt(0)
	v_mfma_f32_32x32x16_bf16 v[32:47], v[68:71], v[64:67], v[32:47]
	v_add_f32_e64 v64, v108, v78
	v_add_f32_e64 v65, v109, v79
	v_add_f32_e64 v66, v122, v76
	v_add_f32_e64 v67, v123, v77
	v_add_f32_e64 v64, v208, v64
	v_add_f32_e64 v65, v209, v65
	v_add_f32_e32 v66, v126, v66
	v_add_f32_e32 v67, v127, v67
	v_add_f32_e32 v64, v110, v64
	v_add_f32_e32 v65, v111, v65
	s_nop 0
	v_add_f32_e32 v64, v66, v64
	v_add_f32_e32 v65, v67, v65
	v_mfma_f32_32x32x16_bf16 v[0:15], v[68:71], v[72:75], v[0:15]
	v_add_f32_e64 v200, v200, v64
	v_add_f32_e64 v201, v201, v65
	s_add_i32 s10, s10, 2
	s_cmpk_lt_i32 s10, 0x7e
	s_cbranch_scc1 .LBB0_1446
	s_waitcnt lgkmcnt(0)
	s_barrier
	ds_read_b128 v[64:67], v215
	ds_read_b128 v[202:205], v215 offset:32
	ds_read_b128 v[68:71], v215 offset:6656
	ds_read_b128 v[206:209], v215 offset:6688
	s_waitcnt lgkmcnt(3)
	v_mfma_f32_32x32x16_bf16 v[112:127], v[64:67], v[128:131], v[236:251]
	s_waitcnt lgkmcnt(1)
	v_mfma_f32_32x32x16_bf16 v[96:111], v[68:71], v[128:131], v[236:251]
	v_mfma_f32_32x32x16_bf16 v[80:95], v[64:67], v[152:155], v[236:251]
	v_mfma_f32_32x32x16_bf16 v[64:79], v[68:71], v[152:155], v[236:251]
	v_mfma_f32_32x32x16_bf16 v[112:127], v[202:205], v[132:135], v[112:127]
	s_waitcnt lgkmcnt(0)
	v_mfma_f32_32x32x16_bf16 v[96:111], v[206:209], v[132:135], v[96:111]
	v_mfma_f32_32x32x16_bf16 v[80:95], v[202:205], v[156:159], v[80:95]
	v_mfma_f32_32x32x16_bf16 v[64:79], v[206:209], v[156:159], v[64:79]
	ds_read_b128 v[202:205], v215 offset:64
	ds_read_b128 v[206:209], v215 offset:96
	ds_read_b128 v[218:221], v215 offset:6720
	ds_read_b128 v[222:225], v215 offset:6752
	s_waitcnt lgkmcnt(3)
	v_mfma_f32_32x32x16_bf16 v[112:127], v[202:205], v[136:139], v[112:127]
	s_waitcnt lgkmcnt(1)
	v_mfma_f32_32x32x16_bf16 v[96:111], v[218:221], v[136:139], v[96:111]
	v_mfma_f32_32x32x16_bf16 v[80:95], v[202:205], v[160:163], v[80:95]
	v_mfma_f32_32x32x16_bf16 v[64:79], v[218:221], v[160:163], v[64:79]
	v_mfma_f32_32x32x16_bf16 v[112:127], v[206:209], v[140:143], v[112:127]
	s_waitcnt lgkmcnt(0)
	v_mfma_f32_32x32x16_bf16 v[96:111], v[222:225], v[140:143], v[96:111]
	v_mfma_f32_32x32x16_bf16 v[80:95], v[206:209], v[164:167], v[80:95]
	ds_read_b128 v[202:205], v215 offset:128
	ds_read_b128 v[206:209], v215 offset:160
	v_mfma_f32_32x32x16_bf16 v[64:79], v[222:225], v[164:167], v[64:79]
	ds_read_b128 v[218:221], v215 offset:6784
	ds_read_b128 v[222:225], v215 offset:6816
	s_waitcnt lgkmcnt(3)
	v_mfma_f32_32x32x16_bf16 v[112:127], v[202:205], v[144:147], v[112:127]
	s_waitcnt lgkmcnt(1)
	v_mfma_f32_32x32x16_bf16 v[96:111], v[218:221], v[144:147], v[96:111]
	v_mfma_f32_32x32x16_bf16 v[80:95], v[202:205], v[168:171], v[80:95]
	v_mfma_f32_32x32x16_bf16 v[64:79], v[218:221], v[168:171], v[64:79]
	v_mfma_f32_32x32x16_bf16 v[112:127], v[206:209], v[148:151], v[112:127]
	s_waitcnt lgkmcnt(0)
	v_mfma_f32_32x32x16_bf16 v[96:111], v[222:225], v[148:151], v[96:111]
	v_mfma_f32_32x32x16_bf16 v[80:95], v[206:209], v[172:175], v[80:95]
	v_mfma_f32_32x32x16_bf16 v[64:79], v[222:225], v[172:175], v[64:79]
	s_waitcnt vmcnt(1)
	ds_write_b128 v212, v[180:183] offset:13312
	s_and_saveexec_b64 s[8:9], vcc
	ds_write_b128 v213, v[176:179] offset:13312
	s_or_b64 exec, exec, s[8:9]
	s_waitcnt vmcnt(0)
	ds_write_b128 v192, v[184:187] offset:35840
	s_nop 2
	v_exp_f32_e32 v96, v96
	v_exp_f32_e32 v112, v112
	v_exp_f32_e32 v208, v97
	v_exp_f32_e32 v204, v113
	v_exp_f32_e32 v227, v99
	v_exp_f32_e32 v114, v114
	v_exp_f32_e32 v116, v116
	v_exp_f32_e32 v217, v98
	v_exp_f32_e32 v100, v100
	v_add_f32_e32 v98, v208, v96
	v_exp_f32_e32 v202, v117
	v_add_f32_e32 v97, v204, v112
	v_exp_f32_e32 v190, v115
	v_exp_f32_e32 v228, v101
	v_exp_f32_e32 v118, v118
	v_add_f32_e32 v98, v217, v98
	v_exp_f32_e32 v229, v102
	v_add_f32_e32 v97, v114, v97
	v_add_f32_e32 v98, v227, v98
	v_add_f32_e32 v97, v190, v97
	v_add_f32_e32 v98, v100, v98
	v_add_f32_e32 v97, v116, v97
	v_add_f32_e32 v98, v228, v98
	v_add_f32_e32 v97, v202, v97
	v_add_f32_e32 v113, v229, v98
	v_add_f32_e32 v115, v118, v97
	v_exp_f32_e32 v203, v119
	v_exp_f32_e32 v119, v121
	v_exp_f32_e32 v117, v105
	v_exp_f32_e32 v99, v122
	v_exp_f32_e32 v101, v106
	v_exp_f32_e32 v205, v103
	v_exp_f32_e32 v103, v123
	v_exp_f32_e32 v105, v107
	v_exp_f32_e32 v107, v124
	v_exp_f32_e32 v121, v108
	v_exp_f32_e32 v125, v125
	v_exp_f32_e32 v109, v109
	v_exp_f32_e32 v123, v126
	v_exp_f32_e32 v209, v110
	v_exp_f32_e32 v127, v127
	v_exp_f32_e32 v98, v80
	v_exp_f32_e32 v102, v81
	v_exp_f32_e32 v108, v65
	v_exp_f32_e32 v207, v120
	v_exp_f32_e32 v97, v104
	v_exp_f32_e32 v104, v64
	v_exp_f32_e32 v106, v82
	v_exp_f32_e32 v111, v111
	v_exp_f32_e32 v110, v66
	v_add_f32_e32 v64, v102, v98
	v_add_f32_e32 v120, v106, v64
	v_add_f32_e32 v65, v108, v104
	v_exp_f32_e32 v231, v83
	v_add_f32_e32 v230, v110, v65
	v_mov_b32_e32 v122, v67
	v_exp_f32_e32 v232, v84
	ds_read_b128 v[64:67], v216 offset:26624
	ds_read_b128 v[218:221], v216 offset:26656
	v_exp_f32_e32 v234, v85
	ds_read_b128 v[222:225], v216 offset:31232
	v_exp_f32_e32 v235, v86
	v_cvt_pk_bf16_f32 v82, v116, v202
	v_exp_f32_e32 v202, v87
	v_cvt_pk_bf16_f32 v80, v112, v204
	v_cvt_pk_bf16_f32 v81, v114, v190
	v_cvt_pk_bf16_f32 v83, v118, v203
	v_cvt_pk_bf16_f32 v84, v98, v102
	v_cvt_pk_bf16_f32 v85, v106, v231
	v_cvt_pk_bf16_f32 v86, v232, v234
	v_cvt_pk_bf16_f32 v87, v235, v202
	s_waitcnt lgkmcnt(2)
; __device__ __forceinline__ float fexp2(float x) { return __builtin_amdgcn_exp2f(x); }
; template <int DQK, int DV>
; __device__ __forceinline__ void attn_pass2(const bf16_t* __restrict__ qh, const bf16_t* __restrict__ kh, const bf16_t* __restrict__ vth, int q0, char* smem, f32x16 (&o)[2][DV / 32], float kmax, int wvp) {
;     ...
;   for (int kt = 0; kt < NT; ++kt) {
;     const int cur = kt & 1;
;     __syncthreads();
;     if (kt + 1 < NT) { STOREKV(cur ^ 1); if (kt + 2 < NT) LOADKV(kt + 2); }
;     f32x16 s[2][2];
;     const char* kb0 = sK + cur * KSB + kofs;
; #pragma unroll
;     for (int ks = 0; ks < NKS; ++ks) {
;       const bf16x8 a0 = *(const bf16x8*)(kb0 + ks * 32), a1 = *(const bf16x8*)(kb0 + 32 * KP + ks * 32);
; #pragma unroll
;       for (int qb = 0; qb < 2; ++qb) {
;         if (ks == 0) {
;           f32x16 z;
; #pragma unroll
;           for (int i = 0; i < 16; ++i) z[i] = 0.f;
;           s[qb][0] = MFMA(a0, qf[qb][0], z); s[qb][1] = MFMA(a1, qf[qb][0], z);
;         } else { s[qb][0] = MFMA(a0, qf[qb][ks], s[qb][0]); s[qb][1] = MFMA(a1, qf[qb][ks], s[qb][1]); }
;       }
;     }
;     __builtin_amdgcn_sched_barrier(0);
; #pragma unroll
;     for (int qb = 0; qb < 2; ++qb) {
;       float rs0 = 0.f, rs1 = 0.f;
; #pragma unroll
;       for (int i = 0; i < 16; ++i) { s[qb][0][i] = fexp2(s[qb][0][i] - mref[qb]); s[qb][1][i] = fexp2(s[qb][1][i] - mref[qb]); rs0 += s[qb][0][i]; rs1 += s[qb][1][i]; }
;       l_run[qb] += rs0 + rs1;
;     }
;     const char* vb0 = sV + cur * VSB + vofs;
; #pragma unroll
;     for (int kb = 0; kb < 2; ++kb)
; #pragma unroll
;       for (int s2 = 0; s2 < 2; ++s2) {
;         bf16x8 pq[2];
; #pragma unroll
;         for (int qb = 0; qb < 2; ++qb) {
;           u32x4 w;
;           w.x = pk2(s[qb][kb][8 * s2 + 0], s[qb][kb][8 * s2 + 1]); w.y = pk2(s[qb][kb][8 * s2 + 2], s[qb][kb][8 * s2 + 3]);
;           w.z = pk2(s[qb][kb][8 * s2 + 4], s[qb][kb][8 * s2 + 5]); w.w = pk2(s[qb][kb][8 * s2 + 6], s[qb][kb][8 * s2 + 7]);
;           pq[qb] = __builtin_bit_cast(bf16x8, w);
;         }
; #pragma unroll
;         for (int eb = 0; eb < NEB; ++eb) {
;           const bf16x8 a = *(const bf16x8*)(vb0 + eb * 32 * VP + (32 * kb + 16 * s2) * 2);
; #pragma unroll
;           for (int qb = 0; qb < 2; ++qb) o[qb][eb] = MFMA(a, pq[qb], o[qb][eb]);
;         }
;       }
;   }
	v_mfma_f32_32x32x16_bf16 v[48:63], v[64:67], v[80:83], v[48:63]
	v_exp_f32_e32 v116, v122
	s_add_u32 s6, s6, 0x3000
	s_addc_u32 s7, s7, 0
	v_mfma_f32_32x32x16_bf16 v[16:31], v[64:67], v[84:87], v[16:31]
	v_exp_f32_e32 v190, v68
	v_exp_f32_e32 v206, v88
	ds_read_b128 v[64:67], v216 offset:31264
	v_exp_f32_e32 v118, v89
	s_waitcnt lgkmcnt(1)
	v_mfma_f32_32x32x16_bf16 v[32:47], v[222:225], v[80:83], v[32:47]
	v_exp_f32_e32 v98, v90
	v_exp_f32_e32 v102, v91
	v_exp_f32_e32 v106, v92
	v_exp_f32_e32 v124, v93
	v_mfma_f32_32x32x16_bf16 v[0:15], v[222:225], v[84:87], v[0:15]
	v_exp_f32_e32 v122, v94
	v_exp_f32_e32 v89, v69
	v_exp_f32_e32 v126, v95
	v_exp_f32_e32 v90, v70
	v_cvt_pk_bf16_f32 v80, v207, v119
	v_cvt_pk_bf16_f32 v81, v99, v103
	v_cvt_pk_bf16_f32 v82, v107, v125
	v_cvt_pk_bf16_f32 v83, v123, v127
	v_add_f32_e32 v68, v231, v120
	v_add_f32_e32 v88, v116, v230
	v_mfma_f32_32x32x16_bf16 v[48:63], v[218:221], v[80:83], v[48:63]
	v_add_f32_e32 v68, v232, v68
	v_add_f32_e32 v88, v190, v88
	v_add_f32_e32 v68, v234, v68
	v_add_f32_e32 v69, v89, v88
	v_cvt_pk_bf16_f32 v84, v206, v118
	v_cvt_pk_bf16_f32 v85, v98, v102
	v_cvt_pk_bf16_f32 v86, v106, v124
	s_waitcnt lgkmcnt(0)
	v_mfma_f32_32x32x16_bf16 v[32:47], v[64:67], v[80:83], v[32:47]
	v_exp_f32_e32 v204, v71
	v_cvt_pk_bf16_f32 v87, v122, v126
	v_add_f32_e32 v114, v235, v68
	v_add_f32_e32 v112, v90, v69
	ds_read_b128 v[68:71], v216 offset:26688
	ds_read_b128 v[80:83], v216 offset:26720
	v_mfma_f32_32x32x16_bf16 v[16:31], v[218:221], v[84:87], v[16:31]
	v_lshl_add_u64 v[194:195], v[194:195], 0, s[54:55]
	v_mfma_f32_32x32x16_bf16 v[0:15], v[64:67], v[84:87], v[0:15]
	v_cvt_pk_bf16_f32 v86, v190, v89
	v_cvt_pk_bf16_f32 v87, v90, v204
	ds_read_b128 v[88:91], v216 offset:31296
	v_cvt_pk_bf16_f32 v64, v96, v208
	v_cvt_pk_bf16_f32 v65, v217, v227
	v_cvt_pk_bf16_f32 v66, v100, v228
	v_cvt_pk_bf16_f32 v67, v229, v205
	v_cvt_pk_bf16_f32 v84, v104, v108
	v_cvt_pk_bf16_f32 v85, v110, v116
	s_waitcnt lgkmcnt(2)
	v_mfma_f32_32x32x16_bf16 v[48:63], v[68:71], v[64:67], v[48:63]
	v_exp_f32_e32 v96, v72
	v_exp_f32_e32 v116, v73
	v_exp_f32_e32 v120, v76
	v_add_f32_e32 v72, v204, v112
	v_add_f32_e32 v73, v205, v113
	v_mfma_f32_32x32x16_bf16 v[16:31], v[68:71], v[84:87], v[16:31]
	v_exp_f32_e32 v100, v74
	v_exp_f32_e32 v104, v75
	ds_read_b128 v[68:71], v216 offset:31328
	v_add_f32_e32 v72, v96, v72
	v_add_f32_e32 v73, v97, v73
	s_waitcnt lgkmcnt(1)
	v_mfma_f32_32x32x16_bf16 v[32:47], v[88:91], v[64:67], v[32:47]
	v_exp_f32_e32 v108, v77
	v_exp_f32_e32 v208, v78
	v_exp_f32_e32 v110, v79
	v_add_f32_e32 v64, v202, v114
	v_add_f32_e32 v65, v203, v115
	v_mfma_f32_32x32x16_bf16 v[0:15], v[88:91], v[84:87], v[0:15]
	v_add_f32_e64 v74, v206, v64
	v_add_f32_e64 v75, v207, v65
	v_cvt_pk_bf16_f32 v64, v97, v117
	v_cvt_pk_bf16_f32 v65, v101, v105
	v_cvt_pk_bf16_f32 v66, v121, v109
	v_cvt_pk_bf16_f32 v67, v209, v111
	v_add_f32_e32 v76, v118, v74
	v_add_f32_e32 v77, v119, v75
	v_add_f32_e32 v78, v116, v72
	v_add_f32_e32 v79, v117, v73
	v_cvt_pk_bf16_f32 v72, v96, v116
	v_cvt_pk_bf16_f32 v73, v100, v104
	v_cvt_pk_bf16_f32 v74, v120, v108
	v_cvt_pk_bf16_f32 v75, v208, v110
	v_mfma_f32_32x32x16_bf16 v[48:63], v[80:83], v[64:67], v[48:63]
	v_add_f32_e64 v76, v98, v76
	v_add_f32_e64 v77, v99, v77
	v_add_f32_e64 v78, v100, v78
	v_add_f32_e64 v79, v101, v79
	v_add_f32_e64 v76, v102, v76
	v_add_f32_e64 v77, v103, v77
	v_add_f32_e32 v78, v104, v78
	v_add_f32_e32 v79, v105, v79
	v_add_f32_e32 v76, v106, v76
	v_add_f32_e32 v77, v107, v77
	v_add_f32_e32 v78, v120, v78
	v_add_f32_e32 v79, v121, v79
	v_add_f32_e32 v76, v124, v76
	v_add_f32_e32 v77, v125, v77
	v_mfma_f32_32x32x16_bf16 v[16:31], v[80:83], v[72:75], v[16:31]
	s_waitcnt lgkmcnt(0)
	v_mfma_f32_32x32x16_bf16 v[32:47], v[68:71], v[64:67], v[32:47]
	v_add_f32_e64 v64, v108, v78
	v_add_f32_e64 v65, v109, v79
	v_add_f32_e64 v66, v122, v76
	v_add_f32_e64 v67, v123, v77
	v_add_f32_e64 v64, v208, v64
	v_add_f32_e64 v65, v209, v65
	v_add_f32_e32 v66, v126, v66
	v_add_f32_e32 v67, v127, v67
	v_add_f32_e32 v64, v110, v64
	v_add_f32_e32 v65, v111, v65
	s_nop 0
	v_add_f32_e32 v64, v66, v64
	v_add_f32_e32 v65, v67, v65
	v_mfma_f32_32x32x16_bf16 v[0:15], v[68:71], v[72:75], v[0:15]
	v_add_f32_e64 v200, v200, v64
	v_add_f32_e64 v201, v201, v65
	s_waitcnt lgkmcnt(0)
	s_barrier
; __device__ __forceinline__ float fexp2(float x) { return __builtin_amdgcn_exp2f(x); }
; template <int DQK, int DV>
; __device__ __forceinline__ void attn_pass2(const bf16_t* __restrict__ qh, const bf16_t* __restrict__ kh, const bf16_t* __restrict__ vth, int q0, char* smem, f32x16 (&o)[2][DV / 32], float kmax, int wvp) {
;     ...
;   for (int kt = 0; kt < NT; ++kt) {
;     const int cur = kt & 1;
;     __syncthreads();
;     if (kt + 1 < NT) { STOREKV(cur ^ 1); if (kt + 2 < NT) LOADKV(kt + 2); }
;     f32x16 s[2][2];
;     const char* kb0 = sK + cur * KSB + kofs;
; #pragma unroll
;     for (int ks = 0; ks < NKS; ++ks) {
;       const bf16x8 a0 = *(const bf16x8*)(kb0 + ks * 32), a1 = *(const bf16x8*)(kb0 + 32 * KP + ks * 32);
; #pragma unroll
;       for (int qb = 0; qb < 2; ++qb) {
;         if (ks == 0) {
;           f32x16 z;
; #pragma unroll
;           for (int i = 0; i < 16; ++i) z[i] = 0.f;
;           s[qb][0] = MFMA(a0, qf[qb][0], z); s[qb][1] = MFMA(a1, qf[qb][0], z);
;         } else { s[qb][0] = MFMA(a0, qf[qb][ks], s[qb][0]); s[qb][1] = MFMA(a1, qf[qb][ks], s[qb][1]); }
;       }
;     }
;     __builtin_amdgcn_sched_barrier(0);
; #pragma unroll
;     for (int qb = 0; qb < 2; ++qb) {
;       float rs0 = 0.f, rs1 = 0.f;
; #pragma unroll
;       for (int i = 0; i < 16; ++i) { s[qb][0][i] = fexp2(s[qb][0][i] - mref[qb]); s[qb][1][i] = fexp2(s[qb][1][i] - mref[qb]); rs0 += s[qb][0][i]; rs1 += s[qb][1][i]; }
;       l_run[qb] += rs0 + rs1;
;     }
;     const char* vb0 = sV + cur * VSB + vofs;
; #pragma unroll
;     for (int kb = 0; kb < 2; ++kb)
; #pragma unroll
;       for (int s2 = 0; s2 < 2; ++s2) {
;         bf16x8 pq[2];
; #pragma unroll
;         for (int qb = 0; qb < 2; ++qb) {
;           u32x4 w;
;           w.x = pk2(s[qb][kb][8 * s2 + 0], s[qb][kb][8 * s2 + 1]); w.y = pk2(s[qb][kb][8 * s2 + 2], s[qb][kb][8 * s2 + 3]);
;           w.z = pk2(s[qb][kb][8 * s2 + 4], s[qb][kb][8 * s2 + 5]); w.w = pk2(s[qb][kb][8 * s2 + 6], s[qb][kb][8 * s2 + 7]);
;           pq[qb] = __builtin_bit_cast(bf16x8, w);
;         }
; #pragma unroll
;         for (int eb = 0; eb < NEB; ++eb) {
;           const bf16x8 a = *(const bf16x8*)(vb0 + eb * 32 * VP + (32 * kb + 16 * s2) * 2);
; #pragma unroll
;           for (int qb = 0; qb < 2; ++qb) o[qb][eb] = MFMA(a, pq[qb], o[qb][eb]);
;         }
;       }
;   }
	ds_read_b128 v[64:67], v215 offset:13312
	ds_read_b128 v[202:205], v215 offset:13344
	ds_read_b128 v[68:71], v215 offset:19968
	ds_read_b128 v[206:209], v215 offset:20000
	s_waitcnt lgkmcnt(3)
	v_mfma_f32_32x32x16_bf16 v[112:127], v[64:67], v[128:131], v[236:251]
	s_waitcnt lgkmcnt(1)
	v_mfma_f32_32x32x16_bf16 v[96:111], v[68:71], v[128:131], v[236:251]
	v_mfma_f32_32x32x16_bf16 v[80:95], v[64:67], v[152:155], v[236:251]
	v_mfma_f32_32x32x16_bf16 v[64:79], v[68:71], v[152:155], v[236:251]
	v_mfma_f32_32x32x16_bf16 v[112:127], v[202:205], v[132:135], v[112:127]
	s_waitcnt lgkmcnt(0)
	v_mfma_f32_32x32x16_bf16 v[96:111], v[206:209], v[132:135], v[96:111]
	v_mfma_f32_32x32x16_bf16 v[80:95], v[202:205], v[156:159], v[80:95]
	v_mfma_f32_32x32x16_bf16 v[64:79], v[206:209], v[156:159], v[64:79]
	ds_read_b128 v[202:205], v215 offset:13376
	ds_read_b128 v[206:209], v215 offset:13408
	ds_read_b128 v[218:221], v215 offset:20032
	ds_read_b128 v[222:225], v215 offset:20064
	s_waitcnt lgkmcnt(3)
	v_mfma_f32_32x32x16_bf16 v[112:127], v[202:205], v[136:139], v[112:127]
	s_waitcnt lgkmcnt(1)
	v_mfma_f32_32x32x16_bf16 v[96:111], v[218:221], v[136:139], v[96:111]
	v_mfma_f32_32x32x16_bf16 v[80:95], v[202:205], v[160:163], v[80:95]
	v_mfma_f32_32x32x16_bf16 v[64:79], v[218:221], v[160:163], v[64:79]
	v_mfma_f32_32x32x16_bf16 v[112:127], v[206:209], v[140:143], v[112:127]
	s_waitcnt lgkmcnt(0)
	v_mfma_f32_32x32x16_bf16 v[96:111], v[222:225], v[140:143], v[96:111]
	v_mfma_f32_32x32x16_bf16 v[80:95], v[206:209], v[164:167], v[80:95]
	ds_read_b128 v[202:205], v215 offset:13440
	ds_read_b128 v[206:209], v215 offset:13472
	v_mfma_f32_32x32x16_bf16 v[64:79], v[222:225], v[164:167], v[64:79]
	ds_read_b128 v[218:221], v215 offset:20096
	ds_read_b128 v[222:225], v215 offset:20128
	s_waitcnt lgkmcnt(3)
	v_mfma_f32_32x32x16_bf16 v[112:127], v[202:205], v[144:147], v[112:127]
	s_waitcnt lgkmcnt(1)
	v_mfma_f32_32x32x16_bf16 v[96:111], v[218:221], v[144:147], v[96:111]
	v_mfma_f32_32x32x16_bf16 v[80:95], v[202:205], v[168:171], v[80:95]
	v_mfma_f32_32x32x16_bf16 v[64:79], v[218:221], v[168:171], v[64:79]
	v_mfma_f32_32x32x16_bf16 v[112:127], v[206:209], v[148:151], v[112:127]
	s_waitcnt lgkmcnt(0)
	v_mfma_f32_32x32x16_bf16 v[96:111], v[222:225], v[148:151], v[96:111]
	v_mfma_f32_32x32x16_bf16 v[80:95], v[206:209], v[172:175], v[80:95]
	v_mfma_f32_32x32x16_bf16 v[64:79], v[222:225], v[172:175], v[64:79]
	s_nop 9
	v_exp_f32_e32 v96, v96
	v_exp_f32_e32 v112, v112
	v_exp_f32_e32 v208, v97
	v_exp_f32_e32 v204, v113
	v_exp_f32_e32 v227, v99
	v_exp_f32_e32 v114, v114
	v_exp_f32_e32 v116, v116
	v_exp_f32_e32 v217, v98
	v_exp_f32_e32 v100, v100
	v_add_f32_e32 v98, v208, v96
	v_exp_f32_e32 v202, v117
	v_add_f32_e32 v97, v204, v112
	v_exp_f32_e32 v190, v115
	v_exp_f32_e32 v228, v101
	v_exp_f32_e32 v118, v118
	v_add_f32_e32 v98, v217, v98
	v_exp_f32_e32 v229, v102
	v_add_f32_e32 v97, v114, v97
	v_add_f32_e32 v98, v227, v98
	v_add_f32_e32 v97, v190, v97
	v_add_f32_e32 v98, v100, v98
	v_add_f32_e32 v97, v116, v97
	v_add_f32_e32 v98, v228, v98
	v_add_f32_e32 v97, v202, v97
	v_add_f32_e32 v113, v229, v98
	v_add_f32_e32 v115, v118, v97
	v_exp_f32_e32 v203, v119
	v_exp_f32_e32 v119, v121
	v_exp_f32_e32 v117, v105
	v_exp_f32_e32 v99, v122
	v_exp_f32_e32 v101, v106
	v_exp_f32_e32 v205, v103
	v_exp_f32_e32 v103, v123
	v_exp_f32_e32 v105, v107
	v_exp_f32_e32 v107, v124
	v_exp_f32_e32 v121, v108
	v_exp_f32_e32 v125, v125
	v_exp_f32_e32 v109, v109
	v_exp_f32_e32 v123, v126
	v_exp_f32_e32 v209, v110
	v_exp_f32_e32 v127, v127
	v_exp_f32_e32 v98, v80
	v_exp_f32_e32 v102, v81
	v_exp_f32_e32 v108, v65
	v_exp_f32_e32 v207, v120
	v_exp_f32_e32 v97, v104
	v_exp_f32_e32 v104, v64
	v_exp_f32_e32 v106, v82
	v_exp_f32_e32 v111, v111
	v_exp_f32_e32 v110, v66
	v_add_f32_e32 v64, v102, v98
	v_add_f32_e32 v120, v106, v64
	v_add_f32_e32 v65, v108, v104
	v_exp_f32_e32 v231, v83
	v_add_f32_e32 v230, v110, v65
	v_mov_b32_e32 v122, v67
	v_exp_f32_e32 v232, v84
	ds_read_b128 v[64:67], v216 offset:35840
	ds_read_b128 v[218:221], v216 offset:35872
	v_exp_f32_e32 v234, v85
	ds_read_b128 v[222:225], v216 offset:40448
	v_exp_f32_e32 v235, v86
	v_cvt_pk_bf16_f32 v82, v116, v202
	v_exp_f32_e32 v202, v87
	v_cvt_pk_bf16_f32 v80, v112, v204
	v_cvt_pk_bf16_f32 v81, v114, v190
	v_cvt_pk_bf16_f32 v83, v118, v203
	v_cvt_pk_bf16_f32 v84, v98, v102
	v_cvt_pk_bf16_f32 v85, v106, v231
	v_cvt_pk_bf16_f32 v86, v232, v234
	v_cvt_pk_bf16_f32 v87, v235, v202
	s_waitcnt lgkmcnt(2)
; __device__ __forceinline__ float fexp2(float x) { return __builtin_amdgcn_exp2f(x); }
; template <int DQK, int DV>
; __device__ __forceinline__ void attn_pass2(const bf16_t* __restrict__ qh, const bf16_t* __restrict__ kh, const bf16_t* __restrict__ vth, int q0, char* smem, f32x16 (&o)[2][DV / 32], float kmax, int wvp) {
;     ...
;   for (int kt = 0; kt < NT; ++kt) {
;     const int cur = kt & 1;
;     __syncthreads();
;     if (kt + 1 < NT) { STOREKV(cur ^ 1); if (kt + 2 < NT) LOADKV(kt + 2); }
;     f32x16 s[2][2];
;     const char* kb0 = sK + cur * KSB + kofs;
; #pragma unroll
;     for (int ks = 0; ks < NKS; ++ks) {
;       const bf16x8 a0 = *(const bf16x8*)(kb0 + ks * 32), a1 = *(const bf16x8*)(kb0 + 32 * KP + ks * 32);
; #pragma unroll
;       for (int qb = 0; qb < 2; ++qb) {
;         if (ks == 0) {
;           f32x16 z;
; #pragma unroll
;           for (int i = 0; i < 16; ++i) z[i] = 0.f;
;           s[qb][0] = MFMA(a0, qf[qb][0], z); s[qb][1] = MFMA(a1, qf[qb][0], z);
;         } else { s[qb][0] = MFMA(a0, qf[qb][ks], s[qb][0]); s[qb][1] = MFMA(a1, qf[qb][ks], s[qb][1]); }
;       }
;     }
;     __builtin_amdgcn_sched_barrier(0);
; #pragma unroll
;     for (int qb = 0; qb < 2; ++qb) {
;       float rs0 = 0.f, rs1 = 0.f;
; #pragma unroll
;       for (int i = 0; i < 16; ++i) { s[qb][0][i] = fexp2(s[qb][0][i] - mref[qb]); s[qb][1][i] = fexp2(s[qb][1][i] - mref[qb]); rs0 += s[qb][0][i]; rs1 += s[qb][1][i]; }
;       l_run[qb] += rs0 + rs1;
;     }
;     const char* vb0 = sV + cur * VSB + vofs;
; #pragma unroll
;     for (int kb = 0; kb < 2; ++kb)
; #pragma unroll
;       for (int s2 = 0; s2 < 2; ++s2) {
;         bf16x8 pq[2];
; #pragma unroll
;         for (int qb = 0; qb < 2; ++qb) {
;           u32x4 w;
;           w.x = pk2(s[qb][kb][8 * s2 + 0], s[qb][kb][8 * s2 + 1]); w.y = pk2(s[qb][kb][8 * s2 + 2], s[qb][kb][8 * s2 + 3]);
;           w.z = pk2(s[qb][kb][8 * s2 + 4], s[qb][kb][8 * s2 + 5]); w.w = pk2(s[qb][kb][8 * s2 + 6], s[qb][kb][8 * s2 + 7]);
;           pq[qb] = __builtin_bit_cast(bf16x8, w);
;         }
; #pragma unroll
;         for (int eb = 0; eb < NEB; ++eb) {
;           const bf16x8 a = *(const bf16x8*)(vb0 + eb * 32 * VP + (32 * kb + 16 * s2) * 2);
; #pragma unroll
;           for (int qb = 0; qb < 2; ++qb) o[qb][eb] = MFMA(a, pq[qb], o[qb][eb]);
;         }
;       }
;   }
	v_mfma_f32_32x32x16_bf16 v[48:63], v[64:67], v[80:83], v[48:63]
	v_exp_f32_e32 v116, v122
	s_add_u32 s6, s6, 0x3000
	s_addc_u32 s7, s7, 0
	v_mfma_f32_32x32x16_bf16 v[16:31], v[64:67], v[84:87], v[16:31]
	v_exp_f32_e32 v190, v68
	v_exp_f32_e32 v206, v88
	ds_read_b128 v[64:67], v216 offset:40480
	v_exp_f32_e32 v118, v89
	s_waitcnt lgkmcnt(1)
	v_mfma_f32_32x32x16_bf16 v[32:47], v[222:225], v[80:83], v[32:47]
	v_exp_f32_e32 v98, v90
	v_exp_f32_e32 v102, v91
	v_exp_f32_e32 v106, v92
	v_exp_f32_e32 v124, v93
	v_mfma_f32_32x32x16_bf16 v[0:15], v[222:225], v[84:87], v[0:15]
	v_exp_f32_e32 v122, v94
	v_exp_f32_e32 v89, v69
	v_exp_f32_e32 v126, v95
	v_exp_f32_e32 v90, v70
	v_cvt_pk_bf16_f32 v80, v207, v119
	v_cvt_pk_bf16_f32 v81, v99, v103
	v_cvt_pk_bf16_f32 v82, v107, v125
	v_cvt_pk_bf16_f32 v83, v123, v127
	v_add_f32_e32 v68, v231, v120
	v_add_f32_e32 v88, v116, v230
	v_mfma_f32_32x32x16_bf16 v[48:63], v[218:221], v[80:83], v[48:63]
	v_add_f32_e32 v68, v232, v68
	v_add_f32_e32 v88, v190, v88
	v_add_f32_e32 v68, v234, v68
	v_add_f32_e32 v69, v89, v88
	v_cvt_pk_bf16_f32 v84, v206, v118
	v_cvt_pk_bf16_f32 v85, v98, v102
	v_cvt_pk_bf16_f32 v86, v106, v124
	s_waitcnt lgkmcnt(0)
	v_mfma_f32_32x32x16_bf16 v[32:47], v[64:67], v[80:83], v[32:47]
	v_exp_f32_e32 v204, v71
	v_cvt_pk_bf16_f32 v87, v122, v126
	v_add_f32_e32 v114, v235, v68
	v_add_f32_e32 v112, v90, v69
	ds_read_b128 v[68:71], v216 offset:35904
	ds_read_b128 v[80:83], v216 offset:35936
	v_mfma_f32_32x32x16_bf16 v[16:31], v[218:221], v[84:87], v[16:31]
	v_lshl_add_u64 v[194:195], v[194:195], 0, s[54:55]
	v_mfma_f32_32x32x16_bf16 v[0:15], v[64:67], v[84:87], v[0:15]
	v_cvt_pk_bf16_f32 v86, v190, v89
	v_cvt_pk_bf16_f32 v87, v90, v204
	ds_read_b128 v[88:91], v216 offset:40512
	v_cvt_pk_bf16_f32 v64, v96, v208
	v_cvt_pk_bf16_f32 v65, v217, v227
	v_cvt_pk_bf16_f32 v66, v100, v228
	v_cvt_pk_bf16_f32 v67, v229, v205
	v_cvt_pk_bf16_f32 v84, v104, v108
	v_cvt_pk_bf16_f32 v85, v110, v116
	s_waitcnt lgkmcnt(2)
	v_mfma_f32_32x32x16_bf16 v[48:63], v[68:71], v[64:67], v[48:63]
	v_exp_f32_e32 v96, v72
	v_exp_f32_e32 v116, v73
	v_exp_f32_e32 v120, v76
	v_add_f32_e32 v72, v204, v112
	v_add_f32_e32 v73, v205, v113
	v_mfma_f32_32x32x16_bf16 v[16:31], v[68:71], v[84:87], v[16:31]
	v_exp_f32_e32 v100, v74
	v_exp_f32_e32 v104, v75
	ds_read_b128 v[68:71], v216 offset:40544
	v_add_f32_e32 v72, v96, v72
	v_add_f32_e32 v73, v97, v73
	s_waitcnt lgkmcnt(1)
	v_mfma_f32_32x32x16_bf16 v[32:47], v[88:91], v[64:67], v[32:47]
	v_exp_f32_e32 v108, v77
	v_exp_f32_e32 v208, v78
	v_exp_f32_e32 v110, v79
	v_add_f32_e32 v64, v202, v114
	v_add_f32_e32 v65, v203, v115
	v_mfma_f32_32x32x16_bf16 v[0:15], v[88:91], v[84:87], v[0:15]
	v_add_f32_e64 v74, v206, v64
	v_add_f32_e64 v75, v207, v65
	v_cvt_pk_bf16_f32 v64, v97, v117
	v_cvt_pk_bf16_f32 v65, v101, v105
	v_cvt_pk_bf16_f32 v66, v121, v109
	v_cvt_pk_bf16_f32 v67, v209, v111
	v_add_f32_e32 v76, v118, v74
	v_add_f32_e32 v77, v119, v75
	v_add_f32_e32 v78, v116, v72
	v_add_f32_e32 v79, v117, v73
	v_cvt_pk_bf16_f32 v72, v96, v116
	v_cvt_pk_bf16_f32 v73, v100, v104
	v_cvt_pk_bf16_f32 v74, v120, v108
	v_cvt_pk_bf16_f32 v75, v208, v110
	v_mfma_f32_32x32x16_bf16 v[48:63], v[80:83], v[64:67], v[48:63]
	v_add_f32_e64 v76, v98, v76
	v_add_f32_e64 v77, v99, v77
	v_add_f32_e64 v78, v100, v78
	v_add_f32_e64 v79, v101, v79
	v_add_f32_e64 v76, v102, v76
	v_add_f32_e64 v77, v103, v77
	v_add_f32_e32 v78, v104, v78
	v_add_f32_e32 v79, v105, v79
	v_add_f32_e32 v76, v106, v76
	v_add_f32_e32 v77, v107, v77
	v_add_f32_e32 v78, v120, v78
	v_add_f32_e32 v79, v121, v79
	v_add_f32_e32 v76, v124, v76
	v_add_f32_e32 v77, v125, v77
	v_mfma_f32_32x32x16_bf16 v[16:31], v[80:83], v[72:75], v[16:31]
	s_waitcnt lgkmcnt(0)
	v_mfma_f32_32x32x16_bf16 v[32:47], v[68:71], v[64:67], v[32:47]
	v_add_f32_e64 v64, v108, v78
	v_add_f32_e64 v65, v109, v79
	v_add_f32_e64 v66, v122, v76
	v_add_f32_e64 v67, v123, v77
	v_add_f32_e64 v64, v208, v64
	v_add_f32_e64 v65, v209, v65
	v_add_f32_e32 v66, v126, v66
	v_add_f32_e32 v67, v127, v67
	v_add_f32_e32 v64, v110, v64
	v_add_f32_e32 v65, v111, v65
	s_nop 0
	v_add_f32_e32 v64, v66, v64
	v_add_f32_e32 v65, v67, v65
	v_mfma_f32_32x32x16_bf16 v[0:15], v[68:71], v[72:75], v[0:15]
	v_add_f32_e64 v200, v200, v64
	v_add_f32_e64 v201, v201, v65
	s_branch .LBB0_1425
